# prologue convert_win(layer 0) hand-pipelined: next tile's loads issued before the current tile's stores, counted wait skips the store acks
# speedup vs baseline: 1.0076x; 1.0076x over previous
.LBB0_36:
	s_mov_b64 s[6:7], s[62:63]
	s_cmpk_gt_i32 s64, 0x61f
	s_cbranch_scc1 .LBB0_39
	s_load_dwordx2 s[8:9], s[62:63], 0x20
	s_load_dwordx2 s[10:11], s[62:63], 0xc0
	v_lshrrev_b32_e32 v186, 7, v208
	v_and_b32_e32 v187, 0x7f, v208
	v_mov_b32_e32 v188, 12552
	v_mad_u32_u24 v188, v186, v188, v187
	v_lshlrev_b32_e32 v132, 2, v188
	v_mov_b32_e32 v188, 0x90
	v_mul_u32_u24_e32 v188, v187, v188
	v_lshl_add_u32 v133, v186, 1, v188
	v_lshrrev_b32_e32 v186, 3, v208
	v_and_b32_e32 v187, 7, v208
	v_mov_b32_e32 v188, 0x90
	v_mul_u32_u24_e32 v188, v186, v188
	v_lshl_add_u32 v134, v187, 4, v188
	v_lshlrev_b32_e32 v188, 11, v186
	v_lshl_add_u32 v135, v187, 4, v188
	s_mov_b32 s6, s64
	s_mov_b32 s7, s66
	s_waitcnt lgkmcnt(0)
	s_and_b32 s22, s6, 15
	s_lshl_b32 s22, s22, 6
	s_lshr_b32 s23, s6, 4
	s_lshl_b32 s23, s23, 7
	s_mul_i32 s22, s22, 12552
	s_add_i32 s22, s22, s23
	s_cmpk_ge_u32 s23, 0xa00
	s_cselect_b32 s23, 8, 0
	s_add_i32 s22, s22, s23
	s_lshl_b32 s22, s22, 2
	s_add_u32 s12, s8, s22
	s_addc_u32 s13, s9, 0
	s_mov_b64 s[14:15], s[12:13]
	global_load_dword v136, v132, s[14:15]
	s_add_u32 s14, s14, 200832
	s_addc_u32 s15, s15, 0
	global_load_dword v137, v132, s[14:15]
	s_add_u32 s14, s14, 200832
	s_addc_u32 s15, s15, 0
	global_load_dword v138, v132, s[14:15]
	s_add_u32 s14, s14, 200832
	s_addc_u32 s15, s15, 0
	global_load_dword v139, v132, s[14:15]
	s_add_u32 s14, s14, 200832
	s_addc_u32 s15, s15, 0
	global_load_dword v140, v132, s[14:15]
	s_add_u32 s14, s14, 200832
	s_addc_u32 s15, s15, 0
	global_load_dword v141, v132, s[14:15]
	s_add_u32 s14, s14, 200832
	s_addc_u32 s15, s15, 0
	global_load_dword v142, v132, s[14:15]
	s_add_u32 s14, s14, 200832
	s_addc_u32 s15, s15, 0
	global_load_dword v143, v132, s[14:15]
	s_add_u32 s14, s14, 200832
	s_addc_u32 s15, s15, 0
	global_load_dword v144, v132, s[14:15]
	s_add_u32 s14, s14, 200832
	s_addc_u32 s15, s15, 0
	global_load_dword v145, v132, s[14:15]
	s_add_u32 s14, s14, 200832
	s_addc_u32 s15, s15, 0
	global_load_dword v146, v132, s[14:15]
	s_add_u32 s14, s14, 200832
	s_addc_u32 s15, s15, 0
	global_load_dword v147, v132, s[14:15]
	s_add_u32 s14, s14, 200832
	s_addc_u32 s15, s15, 0
	global_load_dword v148, v132, s[14:15]
	s_add_u32 s14, s14, 200832
	s_addc_u32 s15, s15, 0
	global_load_dword v149, v132, s[14:15]
	s_add_u32 s14, s14, 200832
	s_addc_u32 s15, s15, 0
	global_load_dword v150, v132, s[14:15]
	s_add_u32 s14, s14, 200832
	s_addc_u32 s15, s15, 0
	global_load_dword v151, v132, s[14:15]
	s_mov_b32 s27, 0
.Lcw0_loop:
	s_add_i32 s26, s6, s7
	s_cmpk_lt_i32 s26, 0x620
	s_cbranch_scc0 .Lcw0_nonext0
	s_and_b32 s22, s26, 15
	s_lshl_b32 s22, s22, 6
	s_lshr_b32 s23, s26, 4
	s_lshl_b32 s23, s23, 7
	s_mul_i32 s22, s22, 12552
	s_add_i32 s22, s22, s23
	s_cmpk_ge_u32 s23, 0xa00
	s_cselect_b32 s23, 8, 0
	s_add_i32 s22, s22, s23
	s_lshl_b32 s22, s22, 2
	s_add_u32 s12, s8, s22
	s_addc_u32 s13, s9, 0
	s_mov_b64 s[14:15], s[12:13]
	global_load_dword v170, v132, s[14:15]
	s_add_u32 s14, s14, 200832
	s_addc_u32 s15, s15, 0
	global_load_dword v171, v132, s[14:15]
	s_add_u32 s14, s14, 200832
	s_addc_u32 s15, s15, 0
	global_load_dword v172, v132, s[14:15]
	s_add_u32 s14, s14, 200832
	s_addc_u32 s15, s15, 0
	global_load_dword v173, v132, s[14:15]
	s_add_u32 s14, s14, 200832
	s_addc_u32 s15, s15, 0
	global_load_dword v174, v132, s[14:15]
	s_add_u32 s14, s14, 200832
	s_addc_u32 s15, s15, 0
	global_load_dword v175, v132, s[14:15]
	s_add_u32 s14, s14, 200832
	s_addc_u32 s15, s15, 0
	global_load_dword v176, v132, s[14:15]
	s_add_u32 s14, s14, 200832
	s_addc_u32 s15, s15, 0
	global_load_dword v177, v132, s[14:15]
	s_add_u32 s14, s14, 200832
	s_addc_u32 s15, s15, 0
	global_load_dword v178, v132, s[14:15]
	s_add_u32 s14, s14, 200832
	s_addc_u32 s15, s15, 0
	global_load_dword v179, v132, s[14:15]
	s_add_u32 s14, s14, 200832
	s_addc_u32 s15, s15, 0
	global_load_dword v180, v132, s[14:15]
	s_add_u32 s14, s14, 200832
	s_addc_u32 s15, s15, 0
	global_load_dword v181, v132, s[14:15]
	s_add_u32 s14, s14, 200832
	s_addc_u32 s15, s15, 0
	global_load_dword v182, v132, s[14:15]
	s_add_u32 s14, s14, 200832
	s_addc_u32 s15, s15, 0
	global_load_dword v183, v132, s[14:15]
	s_add_u32 s14, s14, 200832
	s_addc_u32 s15, s15, 0
	global_load_dword v184, v132, s[14:15]
	s_add_u32 s14, s14, 200832
	s_addc_u32 s15, s15, 0
	global_load_dword v185, v132, s[14:15]
	s_cmp_eq_u32 s27, 0
	s_cbranch_scc1 .Lcw0_first0
	s_waitcnt vmcnt(18)
	s_branch .Lcw0_proc0
.Lcw0_first0:
	s_waitcnt vmcnt(16)
	s_mov_b32 s27, 1
	s_branch .Lcw0_proc0

.Lcw0_proc0:
	v_cvt_pk_bf16_f32 v136, v136, v136
	v_cvt_pk_bf16_f32 v137, v137, v137
	v_cvt_pk_bf16_f32 v138, v138, v138
	v_cvt_pk_bf16_f32 v139, v139, v139
	v_cvt_pk_bf16_f32 v140, v140, v140
	v_cvt_pk_bf16_f32 v141, v141, v141
	v_cvt_pk_bf16_f32 v142, v142, v142
	v_cvt_pk_bf16_f32 v143, v143, v143
	v_cvt_pk_bf16_f32 v144, v144, v144
	v_cvt_pk_bf16_f32 v145, v145, v145
	v_cvt_pk_bf16_f32 v146, v146, v146
	v_cvt_pk_bf16_f32 v147, v147, v147
	v_cvt_pk_bf16_f32 v148, v148, v148
	v_cvt_pk_bf16_f32 v149, v149, v149
	v_cvt_pk_bf16_f32 v150, v150, v150
	v_cvt_pk_bf16_f32 v151, v151, v151
	ds_write_b16 v133, v136 offset:0
	ds_write_b16 v133, v137 offset:8
	ds_write_b16 v133, v138 offset:16
	ds_write_b16 v133, v139 offset:24
	ds_write_b16 v133, v140 offset:32
	ds_write_b16 v133, v141 offset:40
	ds_write_b16 v133, v142 offset:48
	ds_write_b16 v133, v143 offset:56
	ds_write_b16 v133, v144 offset:64
	ds_write_b16 v133, v145 offset:72
	ds_write_b16 v133, v146 offset:80
	ds_write_b16 v133, v147 offset:88
	ds_write_b16 v133, v148 offset:96
	ds_write_b16 v133, v149 offset:104
	ds_write_b16 v133, v150 offset:112
	ds_write_b16 v133, v151 offset:120
	s_and_b32 s22, s6, 15
	s_lshl_b32 s22, s22, 6
	s_lshr_b32 s23, s6, 4
	s_lshl_b32 s23, s23, 17
	s_add_i32 s22, s22, s23
	s_lshl_b32 s22, s22, 1
	s_add_u32 s16, s10, s22
	s_addc_u32 s17, s11, 0
	s_add_u32 s18, s16, 0x20000
	s_addc_u32 s19, s17, 0
	s_waitcnt lgkmcnt(0)
	s_barrier
	ds_read_b128 v[210:213], v134 offset:0
	ds_read_b128 v[214:217], v134 offset:9216
	s_waitcnt lgkmcnt(1)
	global_store_dwordx4 v135, v[210:213], s[16:17]
	s_waitcnt lgkmcnt(0)
	global_store_dwordx4 v135, v[214:217], s[18:19]
	s_mov_b32 s6, s26
	s_cmpk_lt_i32 s6, 0x620
	s_cbranch_scc0 .Lcw0_done
	s_add_i32 s26, s6, s7
	s_cmpk_lt_i32 s26, 0x620
	s_cbranch_scc0 .Lcw0_nonext1
	s_and_b32 s22, s26, 15
	s_lshl_b32 s22, s22, 6
	s_lshr_b32 s23, s26, 4
	s_lshl_b32 s23, s23, 7
	s_mul_i32 s22, s22, 12552
	s_add_i32 s22, s22, s23
	s_cmpk_ge_u32 s23, 0xa00
	s_cselect_b32 s23, 8, 0
	s_add_i32 s22, s22, s23
	s_lshl_b32 s22, s22, 2
	s_add_u32 s12, s8, s22
	s_addc_u32 s13, s9, 0
	s_mov_b64 s[14:15], s[12:13]
	global_load_dword v136, v132, s[14:15]
	s_add_u32 s14, s14, 200832
	s_addc_u32 s15, s15, 0
	global_load_dword v137, v132, s[14:15]
	s_add_u32 s14, s14, 200832
	s_addc_u32 s15, s15, 0
	global_load_dword v138, v132, s[14:15]
	s_add_u32 s14, s14, 200832
	s_addc_u32 s15, s15, 0
	global_load_dword v139, v132, s[14:15]
	s_add_u32 s14, s14, 200832
	s_addc_u32 s15, s15, 0
	global_load_dword v140, v132, s[14:15]
	s_add_u32 s14, s14, 200832
	s_addc_u32 s15, s15, 0
	global_load_dword v141, v132, s[14:15]
	s_add_u32 s14, s14, 200832
	s_addc_u32 s15, s15, 0
	global_load_dword v142, v132, s[14:15]
	s_add_u32 s14, s14, 200832
	s_addc_u32 s15, s15, 0
	global_load_dword v143, v132, s[14:15]
	s_add_u32 s14, s14, 200832
	s_addc_u32 s15, s15, 0
	global_load_dword v144, v132, s[14:15]
	s_add_u32 s14, s14, 200832
	s_addc_u32 s15, s15, 0
	global_load_dword v145, v132, s[14:15]
	s_add_u32 s14, s14, 200832
	s_addc_u32 s15, s15, 0
	global_load_dword v146, v132, s[14:15]
	s_add_u32 s14, s14, 200832
	s_addc_u32 s15, s15, 0
	global_load_dword v147, v132, s[14:15]
	s_add_u32 s14, s14, 200832
	s_addc_u32 s15, s15, 0
	global_load_dword v148, v132, s[14:15]
	s_add_u32 s14, s14, 200832
	s_addc_u32 s15, s15, 0
	global_load_dword v149, v132, s[14:15]
	s_add_u32 s14, s14, 200832
	s_addc_u32 s15, s15, 0
	global_load_dword v150, v132, s[14:15]
	s_add_u32 s14, s14, 200832
	s_addc_u32 s15, s15, 0
	global_load_dword v151, v132, s[14:15]
	s_cmp_eq_u32 s27, 0
	s_cbranch_scc1 .Lcw0_first1
	s_waitcnt vmcnt(18)
	s_branch .Lcw0_proc1

.Lcw0_proc1:
	v_cvt_pk_bf16_f32 v170, v170, v170
	v_cvt_pk_bf16_f32 v171, v171, v171
	v_cvt_pk_bf16_f32 v172, v172, v172
	v_cvt_pk_bf16_f32 v173, v173, v173
	v_cvt_pk_bf16_f32 v174, v174, v174
	v_cvt_pk_bf16_f32 v175, v175, v175
	v_cvt_pk_bf16_f32 v176, v176, v176
	v_cvt_pk_bf16_f32 v177, v177, v177
	v_cvt_pk_bf16_f32 v178, v178, v178
	v_cvt_pk_bf16_f32 v179, v179, v179
	v_cvt_pk_bf16_f32 v180, v180, v180
	v_cvt_pk_bf16_f32 v181, v181, v181
	v_cvt_pk_bf16_f32 v182, v182, v182
	v_cvt_pk_bf16_f32 v183, v183, v183
	v_cvt_pk_bf16_f32 v184, v184, v184
	v_cvt_pk_bf16_f32 v185, v185, v185
	ds_write_b16 v133, v170 offset:18432
	ds_write_b16 v133, v171 offset:18440
	ds_write_b16 v133, v172 offset:18448
	ds_write_b16 v133, v173 offset:18456
	ds_write_b16 v133, v174 offset:18464
	ds_write_b16 v133, v175 offset:18472
	ds_write_b16 v133, v176 offset:18480
	ds_write_b16 v133, v177 offset:18488
	ds_write_b16 v133, v178 offset:18496
	ds_write_b16 v133, v179 offset:18504
	ds_write_b16 v133, v180 offset:18512
	ds_write_b16 v133, v181 offset:18520
	ds_write_b16 v133, v182 offset:18528
	ds_write_b16 v133, v183 offset:18536
	ds_write_b16 v133, v184 offset:18544
	ds_write_b16 v133, v185 offset:18552
	s_and_b32 s22, s6, 15
	s_lshl_b32 s22, s22, 6
	s_lshr_b32 s23, s6, 4
	s_lshl_b32 s23, s23, 17
	s_add_i32 s22, s22, s23
	s_lshl_b32 s22, s22, 1
	s_add_u32 s16, s10, s22
	s_addc_u32 s17, s11, 0
	s_add_u32 s18, s16, 0x20000
	s_addc_u32 s19, s17, 0
	s_waitcnt lgkmcnt(0)
	s_barrier
	ds_read_b128 v[210:213], v134 offset:18432
	ds_read_b128 v[214:217], v134 offset:27648
	s_waitcnt lgkmcnt(1)
	global_store_dwordx4 v135, v[210:213], s[16:17]
	s_waitcnt lgkmcnt(0)
	global_store_dwordx4 v135, v[214:217], s[18:19]
	s_mov_b32 s6, s26
	s_cmpk_lt_i32 s6, 0x620
	s_cbranch_scc0 .Lcw0_done
	s_branch .Lcw0_loop
.Lcw0_done:
	s_waitcnt lgkmcnt(0)
	s_barrier
.LBB0_39:
	s_cmp_lg_u32 s66, 0x7fffffff
	s_cbranch_scc1 .LBB0_51
	v_lshrrev_b32_e32 v1, 20, v0
	v_lshrrev_b32_e32 v0, 10, v0
	v_or_b32_e32 v0, v0, v1
	s_movk_i32 s1, 0x3ff
	v_and_or_b32 v0, v0, s1, v208
	v_cmp_eq_u32_e32 vcc, 0, v0
	s_barrier
	s_and_saveexec_b64 s[6:7], vcc
	s_cbranch_execz .LBB0_50
	buffer_wbl2 sc1
	s_waitcnt vmcnt(0)
	s_load_dwordx2 s[4:5], s[4:5], 0x58
	v_mov_b32_e32 v2, 0
	s_mov_b64 s[8:9], exec
	v_mbcnt_lo_u32_b32 v1, s8, 0
	v_mbcnt_hi_u32_b32 v1, s9, v1
	s_waitcnt lgkmcnt(0)
	global_load_dword v0, v2, s[4:5] offset:40
	v_cmp_eq_u32_e32 vcc, 0, v1
	s_and_saveexec_b64 s[10:11], vcc
	s_cbranch_execz .LBB0_43
	s_bcnt1_i32_b64 s1, s[8:9]
	v_mov_b32_e32 v3, s1
	global_atomic_add v3, v2, v3, s[4:5] offset:32 sc0
